# plus the w_in weight conversion loop (N=1696, predicated): 8 row loads in flight together
# speedup vs baseline: 1.0022x; 1.0022x over previous
; DI u16 bf1(float x) { return (u16)(pk2(x, 0.f) & 0xffffu); }
; DI void conv_tile(unsigned char* smem, const int wv, const float* __restrict__ src, u16* __restrict__ dst, int K, int N, int kind, const float* __restrict__ gain, int ktile, int ntile, bool kperm = false) {
;     ...
; #pragma unroll 4
;   for (int i = 0; i < 8; ++i) {
;     const int k = kq * 8 + i;
;     float v = 0.f;
;     if (n < N) { v = src[(size_t)(k0 + k) * N + n]; if (gain) v *= gain[k0 + k]; }
;     T[nl][k] = bf1(v);
;   }
.LBB0_999:
.LBB0_1000:
	v_mov_b32_e32 v212, 0
	v_mov_b32_e32 v213, 0
	v_mov_b32_e32 v214, 0
	v_mov_b32_e32 v215, 0
	v_mov_b32_e32 v216, 0
	v_mov_b32_e32 v217, 0
	v_mov_b32_e32 v218, 0
	v_mov_b32_e32 v219, 0
	v_lshl_add_u64 v[206:207], v[0:1], 0, s[26:27]
	s_mov_b64 s[26:27], 0x1a80
	s_and_saveexec_b64 s[36:37], s[92:93]
	global_load_dword v212, v[206:207], off
	v_lshl_add_u64 v[206:207], v[206:207], 0, s[26:27]
	global_load_dword v213, v[206:207], off
	v_lshl_add_u64 v[206:207], v[206:207], 0, s[26:27]
	global_load_dword v214, v[206:207], off
	v_lshl_add_u64 v[206:207], v[206:207], 0, s[26:27]
	global_load_dword v215, v[206:207], off
	v_lshl_add_u64 v[206:207], v[206:207], 0, s[26:27]
	global_load_dword v216, v[206:207], off
	v_lshl_add_u64 v[206:207], v[206:207], 0, s[26:27]
	global_load_dword v217, v[206:207], off
	v_lshl_add_u64 v[206:207], v[206:207], 0, s[26:27]
	global_load_dword v218, v[206:207], off
	v_lshl_add_u64 v[206:207], v[206:207], 0, s[26:27]
	global_load_dword v219, v[206:207], off
	s_or_b64 exec, exec, s[36:37]
	s_waitcnt vmcnt(0)
	v_cvt_pk_bf16_f32 v212, v212, v213
	v_cvt_pk_bf16_f32 v214, v214, v215
	v_cvt_pk_bf16_f32 v216, v216, v217
	v_cvt_pk_bf16_f32 v218, v218, v219
	ds_write_b32 v102, v212
	ds_write_b32 v102, v214 offset:4
	ds_write_b32 v102, v216 offset:8
	ds_write_b32 v102, v218 offset:12
	v_add_u32_e32 v102, 16, v102
	s_mov_b64 s[26:27], 0xd400
	s_branch .LBB0_1008
